# current best plus the unrolled P0 transpose load loops (32 loads in flight per tile)
# speedup vs baseline: 1.0089x; 1.0089x over previous
.LBB0_84:
	s_cmp_lt_i32 s82, 2
	s_cselect_b64 s[0:1], -1, 0
	s_and_b64 s[0:1], s[0:1], s[2:3]
	s_andn2_b64 vcc, exec, s[0:1]
	s_cbranch_vccnz .LBB0_105
	s_mov_b64 s[2:3], 0
	v_readlane_b32 s26, v254, 0
	v_mov_b32_e32 v0, v230
	v_mov_b32_e32 v8, v230
	s_cmpk_gt_i32 s26, 0x7f
	v_readfirstlane_b32 s27, v8
	s_cbranch_scc1 .LBB0_105
	s_ashr_i32 s28, s26, 31
	s_lshr_b32 s4, s28, 29
	s_add_i32 s8, s26, s4
	s_and_b32 s4, s8, -8
	s_sub_i32 s6, s26, s4
	s_cmp_gt_i32 s6, -1
	s_cbranch_scc0 .LBB0_88
	s_lshl_b32 s7, s6, 4
	s_ashr_i32 s4, s8, 3
	s_cbranch_execz .LBB0_89
	s_branch .LBB0_90
	s_nop 0
	s_nop 0
	s_nop 0
	s_nop 0
	s_nop 0
	s_nop 0
	s_nop 0
	s_nop 0
	s_nop 0
	s_nop 0
	s_nop 0
	s_nop 0
